# HGRN pass A: next-item prefetch block moved from the loop top to after the item's first barrier (same restructuring that helped pass C), on top of m24
# speedup vs baseline: 1.0006x; 1.0006x over previous
; DI float h2f(unsigned short u) { return (float)__builtin_bit_cast(_Float16, u); }
; DI float flog(float x) { return __builtin_amdgcn_logf(x) * 0.6931471805599453f; }
; DI float sigmoidf_(float x) { return frcp(1.f + fexp(-x)); }
; DI void hgA_load(unsigned char* ws, int item, unsigned (&lf)[16], u32x4 (&ivw)[2]) {
;     const int tid = threadIdx.x, b = item >> 10, h = (item >> 6) & 15, c = item & 63, t0 = b * SEQ + c * 64, k = tid & 127, tq = tid >> 7;
;     const bf16_t* LOGF = (const bf16_t*)(ws + WS_LOGF);
; #pragma unroll
;     for (int i = 0; i < 16; ++i) lf[i] = LOGF[(size_t)(t0 + tq * 16 + i) * DM + h * 128 + k];
;     hg_iv_load((const bf16_t*)(ws + WS_IV), item, ivw);
; }
; DI void hgA_item(LAS unsigned char* lds, unsigned char* ws, unsigned char* ob, int item, const unsigned (&lfr)[16], const u32x4 (&ivw)[2], const float* lbp) {
;     ...
;     { const float lbk = lbp[h * 128 + (tid & 127)];
; #pragma unroll
;       for (int i = 0; i < 16; ++i) { const float om = (1.f - lbk) * sigmoidf_(-h2f((unsigned short)lfr[i])); kk[i] = om; lf[i] = flog(1.f - om); } }
;     float cs[16]; float run = 0.f;
; #pragma unroll
;     for (int i = 0; i < 16; ++i) { run += lf[i]; cs[i] = run; }
;     tot[tq * 128 + k] = run;
;     hg_iv_store(VTs, ivw);
;     __syncthreads();
.LBB0_991:
	s_bfe_u32 s10, s37, 0x40006
	v_cvt_f32_f16_e32 v23, v23
	v_cvt_f32_f16_e32 v22, v22
	v_cvt_f32_f16_e32 v17, v17
	v_cvt_f32_f16_e32 v16, v16
	v_cvt_f32_f16_e32 v12, v12
	v_cvt_f32_f16_e32 v11, v11
	v_cvt_f32_f16_e32 v21, v21
	v_cvt_f32_f16_e32 v20, v20
	v_cvt_f32_f16_e32 v19, v19
	v_cvt_f32_f16_e32 v18, v18
	v_mul_f32_e32 v23, 0x3fb8aa3b, v23
	v_mul_f32_e32 v22, 0x3fb8aa3b, v22
	v_mul_f32_e32 v17, 0x3fb8aa3b, v17
	v_mul_f32_e32 v16, 0x3fb8aa3b, v16
	v_exp_f32_e32 v23, v23
	v_exp_f32_e32 v22, v22
	v_exp_f32_e32 v17, v17
	v_exp_f32_e32 v16, v16
	v_mul_f32_e32 v12, 0x3fb8aa3b, v12
	v_mul_f32_e32 v11, 0x3fb8aa3b, v11
	v_mul_f32_e32 v21, 0x3fb8aa3b, v21
	v_mul_f32_e32 v20, 0x3fb8aa3b, v20
	v_mul_f32_e32 v19, 0x3fb8aa3b, v19
	v_mul_f32_e32 v18, 0x3fb8aa3b, v18
	v_exp_f32_e32 v12, v12
	v_exp_f32_e32 v11, v11
	v_exp_f32_e32 v21, v21
	v_exp_f32_e32 v20, v20
	v_cvt_f32_f16_e32 v15, v15
	v_cvt_f32_f16_e32 v14, v14
	v_exp_f32_e32 v19, v19
	v_exp_f32_e32 v25, v18
	v_cvt_f32_f16_e32 v13, v13
	v_cvt_f32_f16_e32 v10, v10
	v_cvt_f32_f16_e32 v9, v9
	v_cvt_f32_f16_e32 v8, v8
	v_add_f32_e32 v23, 1.0, v23
	v_add_f32_e32 v22, 1.0, v22
	v_add_f32_e32 v30, 1.0, v17
	v_add_f32_e32 v31, 1.0, v16
	v_rcp_f32_e32 v16, v23
	v_rcp_f32_e32 v17, v22
	v_rcp_f32_e32 v22, v30
	v_rcp_f32_e32 v23, v31
	v_add_f32_e32 v12, 1.0, v12
	v_add_f32_e32 v18, 1.0, v11
	v_add_f32_e32 v21, 1.0, v21
	v_add_f32_e32 v20, 1.0, v20
	v_mul_f32_e32 v15, 0x3fb8aa3b, v15
	v_mul_f32_e32 v14, 0x3fb8aa3b, v14
	v_add_f32_e32 v29, 1.0, v19
	v_rcp_f32_e32 v11, v12
	v_rcp_f32_e32 v12, v18
	v_rcp_f32_e32 v18, v21
	v_rcp_f32_e32 v19, v20
	v_add_f32_e32 v21, 1.0, v25
	v_mul_f32_e32 v13, 0x3fb8aa3b, v13
	v_mul_f32_e32 v10, 0x3fb8aa3b, v10
	v_mul_f32_e32 v9, 0x3fb8aa3b, v9
	v_mul_f32_e32 v8, 0x3fb8aa3b, v8
	v_exp_f32_e32 v15, v15
	v_exp_f32_e32 v14, v14
	v_rcp_f32_e32 v20, v29
	v_rcp_f32_e32 v21, v21
	v_exp_f32_e32 v13, v13
	v_exp_f32_e32 v10, v10
	v_exp_f32_e32 v9, v9
	v_exp_f32_e32 v8, v8
	ds_write_b128 v55, v[4:7] offset:18432
	v_add_f32_e32 v15, 1.0, v15
	v_add_f32_e32 v14, 1.0, v14
	v_add_f32_e32 v13, 1.0, v13
	v_add_f32_e32 v26, 1.0, v10
	v_add_f32_e32 v27, 1.0, v9
	v_add_f32_e32 v28, 1.0, v8
	v_rcp_f32_e32 v8, v15
	v_rcp_f32_e32 v9, v14
	v_rcp_f32_e32 v10, v13
	v_rcp_f32_e32 v13, v26
	s_waitcnt vmcnt(0)
	v_sub_f32_e32 v24, 1.0, v100
	v_pk_mul_f32 v[4:5], v[22:23], v[24:25] op_sel_hi:[1,0]
	v_pk_mul_f32 v[18:19], v[18:19], v[24:25] op_sel_hi:[1,0]
	v_sub_f32_e32 v6, 1.0, v4
	v_log_f32_e32 v22, v6
	v_sub_f32_e32 v6, 1.0, v5
	v_log_f32_e32 v23, v6
	v_pk_mul_f32 v[6:7], v[20:21], v[24:25] op_sel_hi:[1,0]
	v_sub_f32_e32 v25, 1.0, v18
	v_log_f32_e32 v25, v25
	v_rcp_f32_e32 v14, v27
	v_rcp_f32_e32 v15, v28
	v_sub_f32_e32 v26, 1.0, v19
	v_pk_mul_f32 v[8:9], v[8:9], v[24:25] op_sel_hi:[1,0]
	v_pk_mul_f32 v[16:17], v[16:17], v[24:25] op_sel_hi:[1,0]
	v_pk_mul_f32 v[14:15], v[14:15], v[24:25] op_sel_hi:[1,0]
	v_pk_mul_f32 v[12:13], v[12:13], v[24:25] op_sel_hi:[1,0]
	v_pk_mul_f32 v[10:11], v[10:11], v[24:25] op_sel_hi:[1,0]
	v_sub_f32_e32 v24, 1.0, v8
	v_log_f32_e32 v24, v24
	v_sub_f32_e32 v76, 1.0, v9
	v_sub_f32_e32 v75, 1.0, v10
	v_log_f32_e32 v76, v76
	v_log_f32_e32 v75, v75
	v_sub_f32_e32 v77, 1.0, v11
	v_sub_f32_e32 v31, 1.0, v12
	v_log_f32_e32 v77, v77
	v_log_f32_e32 v31, v31
	v_sub_f32_e32 v40, 1.0, v13
	v_fma_f32 v78, v24, s3, 0
	v_sub_f32_e32 v29, 1.0, v14
	v_log_f32_e32 v40, v40
	v_fmamk_f32 v76, v76, 0x3f317218, v78
	v_log_f32_e32 v29, v29
	v_sub_f32_e32 v30, 1.0, v15
	v_fmamk_f32 v75, v75, 0x3f317218, v76
	v_sub_f32_e32 v27, 1.0, v16
	v_log_f32_e32 v30, v30
	v_fmamk_f32 v77, v77, 0x3f317218, v75
	v_log_f32_e32 v27, v27
	v_sub_f32_e32 v28, 1.0, v17
	v_fmamk_f32 v31, v31, 0x3f317218, v77
	v_log_f32_e32 v28, v28
	v_fmamk_f32 v40, v40, 0x3f317218, v31
	v_fmamk_f32 v29, v29, 0x3f317218, v40
	v_sub_f32_e32 v20, 1.0, v6
	v_log_f32_e32 v26, v26
	v_fmamk_f32 v30, v30, 0x3f317218, v29
	v_log_f32_e32 v20, v20
	v_sub_f32_e32 v21, 1.0, v7
	v_fmamk_f32 v79, v27, 0x3f317218, v30
	v_log_f32_e32 v21, v21
	v_fmamk_f32 v28, v28, 0x3f317218, v79
	v_fmamk_f32 v80, v25, 0x3f317218, v28
	v_fmamk_f32 v81, v26, 0x3f317218, v80
	v_fmamk_f32 v82, v20, 0x3f317218, v81
	v_fmamk_f32 v83, v21, 0x3f317218, v82
	v_fmamk_f32 v84, v22, 0x3f317218, v83
	v_fmamk_f32 v21, v23, 0x3f317218, v84
	ds_write_b32 v52, v21 offset:36864
	ds_write_b128 v56, v[0:3] offset:18432
	s_waitcnt lgkmcnt(0)
	s_barrier
	s_cselect_b32 s44, 1, 0
	s_and_b64 vcc, exec, s[16:17]
	s_cbranch_vccnz .Lp7_pfskip
	s_and_b32 s42, s23, 0xfffff000
	s_and_b32 s43, s27, 0xfc0
	s_or_b32 s42, s42, s43
	v_readlane_b32 s43, v254, 3
	s_nop 0
	s_lshl_b32 s43, s43, 3
	s_and_b32 s43, s43, 48
	s_add_i32 s42, s42, s43
	s_lshl_b32 s40, s42, 12
	s_and_b32 s42, s29, 0x780
	s_lshl_b32 s42, s42, 1
	s_add_u32 s40, s40, s42
	s_add_u32 s40, s40, 0x8c80000
	s_add_u32 s40, s82, s40
	s_addc_u32 s41, s83, 0
	v_lshlrev_b32_e32 v101, 1, v45
	global_load_ushort v59, v101, s[40:41]
	s_add_u32 s40, s40, 0x1000
	s_addc_u32 s41, s41, 0
	global_load_ushort v60, v101, s[40:41]
	s_add_u32 s40, s40, 0x1000
	s_addc_u32 s41, s41, 0
	global_load_ushort v61, v101, s[40:41]
	s_add_u32 s40, s40, 0x1000
	s_addc_u32 s41, s41, 0
	global_load_ushort v62, v101, s[40:41]
	s_add_u32 s40, s40, 0x1000
	s_addc_u32 s41, s41, 0
	global_load_ushort v63, v101, s[40:41]
	s_add_u32 s40, s40, 0x1000
	s_addc_u32 s41, s41, 0
	global_load_ushort v64, v101, s[40:41]
	s_add_u32 s40, s40, 0x1000
	s_addc_u32 s41, s41, 0
	global_load_ushort v65, v101, s[40:41]
	s_add_u32 s40, s40, 0x1000
	s_addc_u32 s41, s41, 0
	global_load_ushort v66, v101, s[40:41]
	s_add_u32 s40, s40, 0x1000
	s_addc_u32 s41, s41, 0
	global_load_ushort v67, v101, s[40:41]
	s_add_u32 s40, s40, 0x1000
	s_addc_u32 s41, s41, 0
	global_load_ushort v68, v101, s[40:41]
	s_add_u32 s40, s40, 0x1000
	s_addc_u32 s41, s41, 0
	global_load_ushort v69, v101, s[40:41]
	s_add_u32 s40, s40, 0x1000
	s_addc_u32 s41, s41, 0
	global_load_ushort v70, v101, s[40:41]
	s_add_u32 s40, s40, 0x1000
	s_addc_u32 s41, s41, 0
	global_load_ushort v71, v101, s[40:41]
	s_add_u32 s40, s40, 0x1000
	s_addc_u32 s41, s41, 0
	global_load_ushort v72, v101, s[40:41]
	s_add_u32 s40, s40, 0x1000
	s_addc_u32 s41, s41, 0
	global_load_ushort v73, v101, s[40:41]
	s_add_u32 s40, s40, 0x1000
	s_addc_u32 s41, s41, 0
	global_load_ushort v74, v101, s[40:41]
	v_add_co_u32_e32 v102, vcc, 0xffffe000, v48
	s_nop 1
	v_addc_co_u32_e32 v103, vcc, -1, v49, vcc
	global_load_dwordx4 v[36:39], v[102:103], off
	global_load_dwordx4 v[32:35], v[48:49], off
; #define LAS __attribute__((address_space(3)))
; DI unsigned pk2(float lo, float hi) { f32x2 v = {lo, hi}; bf2_t b = __builtin_convertvector(v, bf2_t); return __builtin_bit_cast(unsigned, b); }
; DI float fexp(float x) { return __builtin_amdgcn_exp2f(x * 1.4426950408889634f); }
; DI void hgA_item(LAS unsigned char* lds, unsigned char* ws, unsigned char* ob, int item, const unsigned (&lfr)[16], const u32x4 (&ivw)[2], const float* lbp) {
;     ...
;     const float t0s = tot[k], t1s = tot[128 + k], t2s = tot[256 + k], t3s = tot[384 + k];
;     const float off = (tq > 0 ? t0s : 0.f) + (tq > 1 ? t1s : 0.f) + (tq > 2 ? t2s : 0.f);
;     const float blast = (t0s + t1s) + (t2s + t3s);
;     {
;         float kt[16];
; #pragma unroll
;         for (int i = 0; i < 16; ++i) kt[i] = kk[i] * fexp(blast - (off + cs[i]));
;         u32x4 w0, w1;
;         w0.x = pk2(kt[0], kt[1]); w0.y = pk2(kt[2], kt[3]); w0.z = pk2(kt[4], kt[5]); w0.w = pk2(kt[6], kt[7]);
;         w1.x = pk2(kt[8], kt[9]); w1.y = pk2(kt[10], kt[11]); w1.z = pk2(kt[12], kt[13]); w1.w = pk2(kt[14], kt[15]);
;         *(LAS u32x4*)(KTs + k * TROW + tq * 32) = w0; *(LAS u32x4*)(KTs + k * TROW + tq * 32 + 16) = w1;
;     }
;     if (tq == 0) ((float*)(ws + WS_DEC))[(size_t)item * 128 + k] = fexp(blast);
.Lp7_pfskip:
	s_cmp_lg_u32 s44, 0
	ds_read2st64_b32 v[0:1], v53 offset0:144 offset1:146
	ds_read2st64_b32 v[2:3], v53 offset0:148 offset1:150
	v_readfirstlane_b32 s38, v253
	s_waitcnt lgkmcnt(1)
	v_cndmask_b32_e64 v20, v0, 0, s[4:5]
	v_cndmask_b32_e64 v22, 0, v1, s[6:7]
	v_add_f32_e32 v23, v20, v22
	s_waitcnt lgkmcnt(0)
	v_cndmask_b32_e64 v25, 0, v2, s[8:9]
	v_mov_b32_e32 v22, v0
	v_mov_b32_e32 v24, v1
	v_pk_add_f32 v[22:23], v[22:23], v[24:25]
	v_add_f32_e32 v20, v2, v3
	v_pk_add_f32 v[0:1], v[22:23], v[20:21]
	v_add_f32_e32 v22, v31, v23
	v_sub_f32_e32 v22, v0, v22
	v_mul_f32_e32 v22, 0x3fb8aa3b, v22
	v_exp_f32_e32 v24, v22
	v_add_f32_e32 v22, v23, v40
	v_sub_f32_e32 v22, v0, v22
	v_mul_f32_e32 v22, 0x3fb8aa3b, v22
	v_exp_f32_e32 v25, v22
	v_add_f32_e32 v22, v23, v29
	v_sub_f32_e32 v22, v0, v22
	v_add_f32_e32 v2, v78, v23
	v_add_f32_e32 v3, v76, v23
	v_add_f32_e32 v20, v75, v23
	v_add_f32_e32 v21, v77, v23
	v_mul_f32_e32 v22, 0x3fb8aa3b, v22
	v_sub_f32_e32 v2, v0, v2
	v_sub_f32_e32 v3, v0, v3
	v_sub_f32_e32 v20, v0, v20
	v_sub_f32_e32 v21, v0, v21
	v_exp_f32_e32 v26, v22
	v_add_f32_e32 v22, v23, v30
	v_mul_f32_e32 v2, 0x3fb8aa3b, v2
	v_mul_f32_e32 v3, 0x3fb8aa3b, v3
	v_mul_f32_e32 v20, 0x3fb8aa3b, v20
	v_mul_f32_e32 v21, 0x3fb8aa3b, v21
	v_sub_f32_e32 v22, v0, v22
	v_exp_f32_e32 v2, v2
	v_exp_f32_e32 v3, v3
	v_exp_f32_e32 v20, v20
	v_exp_f32_e32 v21, v21
	v_mul_f32_e32 v22, 0x3fb8aa3b, v22
	v_exp_f32_e32 v27, v22
	v_add_f32_e32 v22, v23, v82
	v_sub_f32_e32 v22, v0, v22
	v_mul_f32_e32 v22, 0x3fb8aa3b, v22
	v_pk_mul_f32 v[2:3], v[8:9], v[2:3]
	v_pk_mul_f32 v[8:9], v[10:11], v[20:21]
	v_pk_mul_f32 v[10:11], v[12:13], v[24:25]
	v_exp_f32_e32 v24, v22
	v_add_f32_e32 v22, v23, v83
	v_sub_f32_e32 v22, v0, v22
	v_mul_f32_e32 v22, 0x3fb8aa3b, v22
	v_pk_mul_f32 v[12:13], v[14:15], v[26:27]
	v_add_f32_e32 v14, v23, v79
	v_add_f32_e32 v15, v23, v28
	v_add_f32_e32 v20, v23, v80
	v_add_f32_e32 v21, v23, v81
	v_exp_f32_e32 v25, v22
	v_add_f32_e32 v22, v23, v84
	v_sub_f32_e32 v14, v0, v14
	v_sub_f32_e32 v15, v0, v15
	v_sub_f32_e32 v20, v0, v20
	v_sub_f32_e32 v21, v0, v21
	v_sub_f32_e32 v22, v0, v22
	v_sub_f32_e32 v1, v0, v1
	v_mul_f32_e32 v14, 0x3fb8aa3b, v14
	v_mul_f32_e32 v15, 0x3fb8aa3b, v15
	v_mul_f32_e32 v20, 0x3fb8aa3b, v20
	v_mul_f32_e32 v21, 0x3fb8aa3b, v21
	v_mul_f32_e32 v22, 0x3fb8aa3b, v22
	v_mul_f32_e32 v1, 0x3fb8aa3b, v1
	v_exp_f32_e32 v14, v14
	v_exp_f32_e32 v15, v15
	v_exp_f32_e32 v20, v20
	v_exp_f32_e32 v21, v21
	v_exp_f32_e32 v22, v22
	v_exp_f32_e32 v23, v1
	v_pk_mul_f32 v[14:15], v[16:17], v[14:15]
	v_pk_mul_f32 v[16:17], v[18:19], v[20:21]
	v_pk_mul_f32 v[18:19], v[6:7], v[24:25]
	v_pk_mul_f32 v[20:21], v[4:5], v[22:23]
	v_cvt_pk_bf16_f32 v2, v2, v3
	v_cvt_pk_bf16_f32 v3, v8, v9
	v_cvt_pk_bf16_f32 v4, v10, v11
	v_cvt_pk_bf16_f32 v5, v12, v13
	v_cvt_pk_bf16_f32 v6, v14, v15
	v_cvt_pk_bf16_f32 v7, v16, v17
	v_cvt_pk_bf16_f32 v8, v18, v19
	v_cvt_pk_bf16_f32 v9, v20, v21
	ds_write_b128 v57, v[2:5]
	ds_write_b128 v57, v[6:9] offset:16
	s_and_saveexec_b64 s[18:19], s[4:5]
	s_cbranch_execz .LBB0_988
	v_mul_f32_e32 v0, 0x3fb8aa3b, v0
	v_exp_f32_e32 v0, v0
	global_store_dword v[50:51], v0, off
	s_branch .LBB0_988
